# v16 + MLA in-loop tiles half-staggered barrier (as FoX) + skip the marker cooperative-groups grid.sync at entry
# speedup vs baseline: 1.0105x; 1.0055x over previous
; #define LAS __attribute__((address_space(3)))
; __global__ void __launch_bounds__(512, 2) hybrid_fwd(Args args) {
;     extern __shared__ __attribute__((aligned(16))) unsigned char lds_raw[];
;     LAS unsigned char* lds = (LAS unsigned char*)lds_raw;
;     cg::grid_group grid = cg::this_grid();
;     grid.sync();
_Z10hybrid_fwd4Args:
	s_load_dwordx2 s[94:95], s[0:1], 0x70
	s_load_dwordx4 s[4:7], s[0:1], 0x60
	s_load_dword s96, s[0:1], 0x78
	s_add_u32 s12, s0, 0x78
	v_and_b32_e32 v1, 0x3fffffff, v0
	s_mov_b32 s93, s2
	s_waitcnt lgkmcnt(0)
	v_writelane_b32 v254, s4, 0
	s_addc_u32 s13, s1, 0
	v_cmp_eq_u32_e32 vcc, 0, v1
	v_writelane_b32 v254, s5, 1
	v_writelane_b32 v254, s6, 2
	v_writelane_b32 v254, s7, 3
	s_load_dwordx8 s[4:11], s[0:1], 0x40
	s_waitcnt lgkmcnt(0)
	s_barrier
	s_and_saveexec_b64 s[2:3], vcc
	s_branch .LBB0_10
	buffer_wbl2 sc1
	s_load_dwordx2 s[12:13], s[12:13], 0x58
	s_mov_b64 s[14:15], exec
	v_mbcnt_lo_u32_b32 v1, s14, 0
	v_mbcnt_hi_u32_b32 v1, s15, v1
	v_cmp_eq_u32_e32 vcc, 0, v1
	s_waitcnt lgkmcnt(0)
	s_load_dword s18, s[12:13], 0x28
	s_and_saveexec_b64 s[16:17], vcc
	s_cbranch_execz .LBB0_3
	s_bcnt1_i32_b64 s14, s[14:15]
	v_mov_b32_e32 v2, 0
	v_mov_b32_e32 v3, s14
	global_atomic_add v2, v2, v3, s[12:13] offset:32 sc0

; template <int TY> __device__ __forceinline__ void attn_unit(LAS unsigned char* lds, const AttnArgs& a, int b, int h, int qt, int wave_s) {
;     ...
;         } else if (64 * J + 63 > ewlo) {
; #pragma unroll
;             for (int kb = 0; kb < 4; ++kb)
; #pragma unroll
;                 for (int r = 0; r < 4; ++r)
; #pragma unroll
;                     for (int qb = 0; qb < 2; ++qb) s[qb][kb][r] = ((16 * kb + r) <= lim[qb]) ? s[qb][kb][r] : -1e30f;
;         }
.LBB0_704:
	s_bitcmp1_b32 s41, 8
	s_cbranch_scc1 .Lml_h0p1_end
	s_waitcnt lgkmcnt(0)
	s_cmp_ge_u32 s22, s18
	s_cbranch_scc1 .Lml_h0p1_bar
	s_waitcnt vmcnt(5)
	ds_write_b128 v208, v[66:69] offset:22784
	s_and_saveexec_b64 s[100:101], s[4:5]
	s_cbranch_execz .Lml_h0p1_w
	v_add_u32_e32 v232, 0, v209
	s_waitcnt vmcnt(3)
	ds_write_b128 v232, v[74:77] offset:24832
.Lml_h0p1_w:
	s_or_b64 exec, exec, s[100:101]
	s_waitcnt vmcnt(4)
	ds_write_b128 v210, v[70:73] offset:35072
.Lml_h0p1_bar:
	s_waitcnt lgkmcnt(0)
	s_barrier
.Lml_h0p1_end:
	s_andn2_b64 vcc, exec, s[8:9]
	s_cbranch_vccnz .LBB0_706
	v_add_u32_e32 v164, 64, v162
	v_add_u32_e32 v163, 0x50, v162
	v_cmp_lt_i32_e32 vcc, -1, v164
	s_nop 1
	v_cndmask_b32_e32 v130, v205, v130, vcc
	v_cmp_lt_i32_e32 vcc, -1, v163
	s_nop 1
	v_cndmask_b32_e32 v10, v205, v10, vcc
	v_cmp_lt_i32_e32 vcc, 0, v164
	s_nop 1
	v_cndmask_b32_e32 v131, v205, v131, vcc
	v_cmp_lt_i32_e32 vcc, 0, v163
	s_nop 1
	v_cndmask_b32_e32 v11, v205, v11, vcc
	v_cmp_lt_i32_e32 vcc, 1, v164
	s_nop 1
	v_cndmask_b32_e32 v132, v205, v132, vcc
	v_cmp_lt_i32_e32 vcc, 1, v163
	s_nop 1
	v_cndmask_b32_e32 v12, v205, v12, vcc
	v_cmp_lt_i32_e32 vcc, 2, v164
	s_nop 1
	v_cndmask_b32_e32 v133, v205, v133, vcc
	v_cmp_lt_i32_e32 vcc, 2, v163
	s_nop 1
	v_cndmask_b32_e32 v13, v205, v13, vcc
	v_cmp_lt_i32_e32 vcc, 15, v164
	s_nop 1
	v_cndmask_b32_e32 v146, v205, v146, vcc
	v_cmp_lt_i32_e32 vcc, 15, v163
	s_nop 1
	v_cndmask_b32_e32 v106, v205, v106, vcc
	v_cmp_lt_i32_e32 vcc, 16, v164
	s_nop 1
	v_cndmask_b32_e32 v147, v205, v147, vcc
	v_cmp_lt_i32_e32 vcc, 16, v163
	s_nop 1
	v_cndmask_b32_e32 v107, v205, v107, vcc
	v_cmp_lt_i32_e32 vcc, 17, v164
	s_nop 1
	v_cndmask_b32_e32 v148, v205, v148, vcc
	v_cmp_lt_i32_e32 vcc, 17, v163
	s_nop 1
	v_cndmask_b32_e32 v108, v205, v108, vcc
	v_cmp_lt_i32_e32 vcc, 18, v164
	s_nop 1
	v_cndmask_b32_e32 v149, v205, v149, vcc
	v_cmp_lt_i32_e32 vcc, 18, v163
	s_nop 1
	v_cndmask_b32_e32 v109, v205, v109, vcc
	v_cmp_lt_i32_e32 vcc, 31, v164
	s_nop 1
	v_cndmask_b32_e32 v154, v205, v154, vcc
	v_cmp_lt_i32_e32 vcc, 31, v163
	s_nop 1
	v_cndmask_b32_e32 v126, v205, v126, vcc
	v_cmp_lt_i32_e32 vcc, 32, v164
	s_nop 1
	v_cndmask_b32_e32 v155, v205, v155, vcc
	v_cmp_lt_i32_e32 vcc, 32, v163
	s_nop 1
	v_cndmask_b32_e32 v127, v205, v127, vcc
	v_cmp_lt_i32_e32 vcc, 33, v164
	s_nop 1
	v_cndmask_b32_e32 v156, v205, v156, vcc
	v_cmp_lt_i32_e32 vcc, 33, v163
	s_nop 1
	v_cndmask_b32_e32 v128, v205, v128, vcc
	v_cmp_lt_i32_e32 vcc, 34, v164
	s_nop 1
	v_cndmask_b32_e32 v157, v205, v157, vcc
	v_cmp_lt_i32_e32 vcc, 34, v163
	s_nop 1
	v_cndmask_b32_e32 v129, v205, v129, vcc
	v_cmp_lt_i32_e32 vcc, 47, v164
	s_nop 1
	v_cndmask_b32_e32 v14, v205, v14, vcc
	v_cmp_lt_i32_e32 vcc, 47, v163
	s_nop 1
	v_cndmask_b32_e32 v134, v205, v134, vcc
	v_cmp_lt_i32_e32 vcc, 48, v164
	s_nop 1
	v_cndmask_b32_e32 v15, v205, v15, vcc
	v_cmp_lt_i32_e32 vcc, 48, v163
	s_nop 1
	v_cndmask_b32_e32 v135, v205, v135, vcc
	v_cmp_lt_i32_e32 vcc, 49, v164
	s_nop 1
	v_cndmask_b32_e32 v16, v205, v16, vcc
	v_cmp_lt_i32_e32 vcc, 49, v163
	s_nop 1
	v_cndmask_b32_e32 v136, v205, v136, vcc
	v_cmp_lt_i32_e32 vcc, 50, v164
	s_nop 1
	v_cndmask_b32_e32 v17, v205, v17, vcc
	v_cmp_lt_i32_e32 vcc, 50, v163
	s_nop 1
	v_cndmask_b32_e32 v137, v205, v137, vcc

; __device__ __forceinline__ unsigned cvt_pk_bf16(float lo, float hi) { f32x2 v = {lo, hi}; bf16x2_t b = __builtin_convertvector(v, bf16x2_t); return __builtin_bit_cast(unsigned, b); }
; template <int TY> __device__ __forceinline__ void attn_unit(LAS unsigned char* lds, const AttnArgs& a, int b, int h, int qt, int wave_s) {
;     ...
; #pragma unroll
;         for (int qb = 0; qb < 2; ++qb) {
; #pragma unroll
;             for (int kb = 0; kb < 4; ++kb)
; #pragma unroll
;                 for (int r = 0; r < 4; ++r) s[qb][kb][r] = __builtin_amdgcn_exp2f(s[qb][kb][r]);
; #pragma unroll
;             for (int G = 0; G < 2; ++G) {
;                 u32x4 w; w.x = cvt_pk_bf16(s[qb][2 * G][0], s[qb][2 * G][1]); w.y = cvt_pk_bf16(s[qb][2 * G][2], s[qb][2 * G][3]);
;                 w.z = cvt_pk_bf16(s[qb][2 * G + 1][0], s[qb][2 * G + 1][1]); w.w = cvt_pk_bf16(s[qb][2 * G + 1][2], s[qb][2 * G + 1][3]);
;                 pf[qb][G] = __builtin_bit_cast(bf16x8, w);
;             }
;         }
.LBB0_708:
	v_exp_f32_e32 v130, v130
	v_exp_f32_e32 v131, v131
	v_exp_f32_e32 v132, v132
	v_exp_f32_e32 v133, v133
	v_exp_f32_e32 v146, v146
	v_exp_f32_e32 v147, v147
	v_exp_f32_e32 v148, v148
	v_exp_f32_e32 v149, v149
	v_exp_f32_e32 v163, v14
	v_exp_f32_e32 v164, v15
	v_cvt_pk_bf16_f32 v130, v130, v131
	v_exp_f32_e32 v10, v10
	v_exp_f32_e32 v11, v11
	v_exp_f32_e32 v12, v12
	v_exp_f32_e32 v13, v13
	v_exp_f32_e32 v14, v106
	v_exp_f32_e32 v15, v107
	v_exp_f32_e32 v106, v108
	v_exp_f32_e32 v107, v109
	v_exp_f32_e32 v108, v126
	v_exp_f32_e32 v109, v127
	v_exp_f32_e32 v126, v128
	v_exp_f32_e32 v127, v129
	v_exp_f32_e32 v128, v134
	v_exp_f32_e32 v131, v136
	v_exp_f32_e32 v134, v137
	v_exp_f32_e32 v154, v154
	v_exp_f32_e32 v155, v155
	v_exp_f32_e32 v156, v156
	v_exp_f32_e32 v157, v157
	v_exp_f32_e32 v129, v135
	v_cvt_pk_bf16_f32 v10, v10, v11
	v_cvt_pk_bf16_f32 v11, v12, v13
	v_cvt_pk_bf16_f32 v12, v14, v15
	v_cvt_pk_bf16_f32 v13, v106, v107
	v_cvt_pk_bf16_f32 v106, v108, v109
	v_cvt_pk_bf16_f32 v107, v126, v127
	v_cvt_pk_bf16_f32 v109, v131, v134
	v_cvt_pk_bf16_f32 v131, v132, v133
	v_cvt_pk_bf16_f32 v132, v146, v147
	v_cvt_pk_bf16_f32 v133, v148, v149
	v_exp_f32_e32 v126, v16
	v_exp_f32_e32 v17, v17
	s_bitcmp1_b32 s41, 8
	s_cbranch_scc0 .Lml_h0p2_end
	s_cmp_ge_u32 s22, s18
	s_cbranch_scc1 .Lml_h0p2_bar
	s_waitcnt vmcnt(5)
	ds_write_b128 v208, v[66:69] offset:22784
	s_and_saveexec_b64 s[100:101], s[4:5]
	s_cbranch_execz .Lml_h0p2_w
	v_add_u32_e32 v232, 0, v209
	s_waitcnt vmcnt(3)
	ds_write_b128 v232, v[74:77] offset:24832

; template <int TY> __device__ __forceinline__ void attn_unit(LAS unsigned char* lds, const AttnArgs& a, int b, int h, int qt, int wave_s) {
;     ...
; #pragma unroll
;         for (int G = 0; G < 2; ++G) {
;             lacc[0] = __builtin_amdgcn_mfma_f32_16x16x32_bf16(ones, pf[0][G], lacc[0], 0, 0, 0);
;             lacc[1] = __builtin_amdgcn_mfma_f32_16x16x32_bf16(ones, pf[1][G], lacc[1], 0, 0, 0);
;         }
; #pragma unroll
;         for (int db = 0; db < 4; ++db)
; #pragma unroll
;             for (int G = 0; G < 2; ++G) {
;                 o[0][db] = __builtin_amdgcn_mfma_f32_16x16x32_bf16(vf[db][G], pf[0][G], o[0][db], 0, 0, 0);
;                 o[1][db] = __builtin_amdgcn_mfma_f32_16x16x32_bf16(vf[db][G], pf[1][G], o[1][db], 0, 0, 0);
;             }
.Lml_h0p2_end:
	v_mfma_f32_16x16x32_bf16 v[6:9], v[54:57], v[10:13], v[6:9]
	v_cvt_pk_bf16_f32 v108, v128, v129
	v_cvt_pk_bf16_f32 v14, v154, v155
	v_cvt_pk_bf16_f32 v15, v156, v157
	s_waitcnt lgkmcnt(13)
	v_mfma_f32_16x16x32_bf16 v[102:105], v[122:125], v[130:133], v[102:105]
	v_cvt_pk_bf16_f32 v16, v163, v164
	v_cvt_pk_bf16_f32 v17, v126, v17
	v_mfma_f32_16x16x32_bf16 v[34:37], v[122:125], v[10:13], v[34:37]
	s_waitcnt lgkmcnt(10)
	v_mfma_f32_16x16x32_bf16 v[98:101], v[110:113], v[130:133], v[98:101]
	v_mfma_f32_16x16x32_bf16 v[30:33], v[110:113], v[10:13], v[30:33]
	s_waitcnt lgkmcnt(6)
	v_mfma_f32_16x16x32_bf16 v[94:97], v[142:145], v[130:133], v[94:97]
	v_mfma_f32_16x16x32_bf16 v[26:29], v[142:145], v[10:13], v[26:29]
	s_waitcnt lgkmcnt(2)
	v_mfma_f32_16x16x32_bf16 v[90:93], v[150:153], v[130:133], v[90:93]
	v_mfma_f32_16x16x32_bf16 v[10:13], v[150:153], v[10:13], v[22:25]
	v_mfma_f32_16x16x32_bf16 v[2:5], v[54:57], v[130:133], v[2:5]
	v_mfma_f32_16x16x32_bf16 v[6:9], v[54:57], v[106:109], v[6:9]
	v_mfma_f32_16x16x32_bf16 v[102:105], v[118:121], v[14:17], v[102:105]
	v_mfma_f32_16x16x32_bf16 v[34:37], v[118:121], v[106:109], v[34:37]
	v_mfma_f32_16x16x32_bf16 v[98:101], v[114:117], v[14:17], v[98:101]
	v_mfma_f32_16x16x32_bf16 v[30:33], v[114:117], v[106:109], v[30:33]
	v_mfma_f32_16x16x32_bf16 v[94:97], v[138:141], v[14:17], v[94:97]
	v_mfma_f32_16x16x32_bf16 v[26:29], v[138:141], v[106:109], v[26:29]
	s_waitcnt lgkmcnt(0)
	v_mfma_f32_16x16x32_bf16 v[90:93], v[158:161], v[14:17], v[90:93]
	v_mfma_f32_16x16x32_bf16 v[22:25], v[158:161], v[106:109], v[10:13]
	v_mfma_f32_16x16x32_bf16 v[2:5], v[54:57], v[14:17], v[2:5]
	s_branch .LBB0_714

; template <int TY> __device__ __forceinline__ void attn_unit(LAS unsigned char* lds, const AttnArgs& a, int b, int h, int qt, int wave_s) {
;     ...
;         } else if (64 * J + 63 > ewlo) {
; #pragma unroll
;             for (int kb = 0; kb < 4; ++kb)
; #pragma unroll
;                 for (int r = 0; r < 4; ++r)
; #pragma unroll
;                     for (int qb = 0; qb < 2; ++qb) s[qb][kb][r] = ((16 * kb + r) <= lim[qb]) ? s[qb][kb][r] : -1e30f;
;         }
.LBB0_719:
	s_bitcmp1_b32 s41, 8
	s_cbranch_scc1 .Lml_h1p1_end
	s_waitcnt lgkmcnt(0)
	s_add_i32 s99, s20, -2
	s_cmp_ge_u32 s99, s18
	s_cbranch_scc1 .Lml_h1p1_bar
	s_waitcnt vmcnt(5)
	ds_write_b128 v208, v[78:81]
	s_and_saveexec_b64 s[100:101], s[4:5]
	s_cbranch_execz .Lml_h1p1_w
	v_add_u32_e32 v232, 0, v209
	s_waitcnt vmcnt(3)
	ds_write_b128 v232, v[86:89] offset:2048
.Lml_h1p1_w:
	s_or_b64 exec, exec, s[100:101]
	s_waitcnt vmcnt(4)
	ds_write_b128 v210, v[82:85] offset:12288
.Lml_h1p1_bar:
	s_waitcnt lgkmcnt(0)
	s_barrier
.Lml_h1p1_end:
	s_andn2_b64 vcc, exec, s[6:7]
	s_cbranch_vccnz .LBB0_721
	v_add_u32_e32 v163, 16, v162
	v_cmp_lt_i32_e32 vcc, -1, v162
	s_nop 1
	v_cndmask_b32_e32 v130, v205, v130, vcc
	v_cmp_lt_i32_e32 vcc, -1, v163
	s_nop 1
	v_cndmask_b32_e32 v10, v205, v10, vcc
	v_cmp_lt_i32_e32 vcc, 0, v162
	s_nop 1
	v_cndmask_b32_e32 v131, v205, v131, vcc
	v_cmp_lt_i32_e32 vcc, 0, v163
	s_nop 1
	v_cndmask_b32_e32 v11, v205, v11, vcc
	v_cmp_lt_i32_e32 vcc, 1, v162
	s_nop 1
	v_cndmask_b32_e32 v132, v205, v132, vcc
	v_cmp_lt_i32_e32 vcc, 1, v163
	s_nop 1
	v_cndmask_b32_e32 v12, v205, v12, vcc
	v_cmp_lt_i32_e32 vcc, 2, v162
	s_nop 1
	v_cndmask_b32_e32 v133, v205, v133, vcc
	v_cmp_lt_i32_e32 vcc, 2, v163
	s_nop 1
	v_cndmask_b32_e32 v13, v205, v13, vcc
	v_cmp_lt_i32_e32 vcc, 15, v162
	s_nop 1
	v_cndmask_b32_e32 v146, v205, v146, vcc
	v_cmp_lt_i32_e32 vcc, 15, v163
	s_nop 1
	v_cndmask_b32_e32 v106, v205, v106, vcc
	v_cmp_lt_i32_e32 vcc, 16, v162
	s_nop 1
	v_cndmask_b32_e32 v147, v205, v147, vcc
	v_cmp_lt_i32_e32 vcc, 16, v163
	s_nop 1
	v_cndmask_b32_e32 v107, v205, v107, vcc
	v_cmp_lt_i32_e32 vcc, 17, v162
	s_nop 1
	v_cndmask_b32_e32 v148, v205, v148, vcc
	v_cmp_lt_i32_e32 vcc, 17, v163
	s_nop 1
	v_cndmask_b32_e32 v108, v205, v108, vcc
	v_cmp_lt_i32_e32 vcc, 18, v162
	s_nop 1
	v_cndmask_b32_e32 v149, v205, v149, vcc
	v_cmp_lt_i32_e32 vcc, 18, v163
	s_nop 1
	v_cndmask_b32_e32 v109, v205, v109, vcc
	v_cmp_lt_i32_e32 vcc, 31, v162
	s_nop 1
	v_cndmask_b32_e32 v154, v205, v154, vcc
	v_cmp_lt_i32_e32 vcc, 31, v163
	s_nop 1
	v_cndmask_b32_e32 v126, v205, v126, vcc
	v_cmp_lt_i32_e32 vcc, 32, v162
	s_nop 1
	v_cndmask_b32_e32 v155, v205, v155, vcc
	v_cmp_lt_i32_e32 vcc, 32, v163
	s_nop 1
	v_cndmask_b32_e32 v127, v205, v127, vcc
	v_cmp_lt_i32_e32 vcc, 33, v162
	s_nop 1
	v_cndmask_b32_e32 v156, v205, v156, vcc
	v_cmp_lt_i32_e32 vcc, 33, v163
	s_nop 1
	v_cndmask_b32_e32 v128, v205, v128, vcc
	v_cmp_lt_i32_e32 vcc, 34, v162
	s_nop 1
	v_cndmask_b32_e32 v157, v205, v157, vcc
	v_cmp_lt_i32_e32 vcc, 34, v163
	s_nop 1
	v_cndmask_b32_e32 v129, v205, v129, vcc
	v_cmp_lt_i32_e32 vcc, 47, v162
	s_nop 1
	v_cndmask_b32_e32 v14, v205, v14, vcc
	v_cmp_lt_i32_e32 vcc, 47, v163
	s_nop 1
	v_cndmask_b32_e32 v134, v205, v134, vcc
	v_cmp_lt_i32_e32 vcc, 48, v162
	s_nop 1
	v_cndmask_b32_e32 v15, v205, v15, vcc
	v_cmp_lt_i32_e32 vcc, 48, v163
	s_nop 1
	v_cndmask_b32_e32 v135, v205, v135, vcc
	v_cmp_lt_i32_e32 vcc, 49, v162
	s_nop 1
	v_cndmask_b32_e32 v16, v205, v16, vcc
	v_cmp_lt_i32_e32 vcc, 49, v163
	s_nop 1
	v_cndmask_b32_e32 v136, v205, v136, vcc
	v_cmp_lt_i32_e32 vcc, 50, v162
	s_nop 1
	v_cndmask_b32_e32 v17, v205, v17, vcc
	v_cmp_lt_i32_e32 vcc, 50, v163
	s_nop 1
	v_cndmask_b32_e32 v137, v205, v137, vcc

; __device__ __forceinline__ unsigned cvt_pk_bf16(float lo, float hi) { f32x2 v = {lo, hi}; bf16x2_t b = __builtin_convertvector(v, bf16x2_t); return __builtin_bit_cast(unsigned, b); }
; template <int TY> __device__ __forceinline__ void attn_unit(LAS unsigned char* lds, const AttnArgs& a, int b, int h, int qt, int wave_s) {
;     ...
; #pragma unroll
;         for (int qb = 0; qb < 2; ++qb) {
; #pragma unroll
;             for (int kb = 0; kb < 4; ++kb)
; #pragma unroll
;                 for (int r = 0; r < 4; ++r) s[qb][kb][r] = __builtin_amdgcn_exp2f(s[qb][kb][r]);
; #pragma unroll
;             for (int G = 0; G < 2; ++G) {
;                 u32x4 w; w.x = cvt_pk_bf16(s[qb][2 * G][0], s[qb][2 * G][1]); w.y = cvt_pk_bf16(s[qb][2 * G][2], s[qb][2 * G][3]);
;                 w.z = cvt_pk_bf16(s[qb][2 * G + 1][0], s[qb][2 * G + 1][1]); w.w = cvt_pk_bf16(s[qb][2 * G + 1][2], s[qb][2 * G + 1][3]);
;                 pf[qb][G] = __builtin_bit_cast(bf16x8, w);
;             }
;         }
.LBB0_723:
	v_exp_f32_e32 v130, v130
	v_exp_f32_e32 v131, v131
	v_exp_f32_e32 v132, v132
	v_exp_f32_e32 v133, v133
	v_exp_f32_e32 v146, v146
	v_exp_f32_e32 v147, v147
	v_exp_f32_e32 v148, v148
	v_exp_f32_e32 v149, v149
	v_exp_f32_e32 v163, v14
	v_exp_f32_e32 v164, v15
	v_cvt_pk_bf16_f32 v130, v130, v131
	v_exp_f32_e32 v10, v10
	v_exp_f32_e32 v11, v11
	v_exp_f32_e32 v12, v12
	v_exp_f32_e32 v13, v13
	v_exp_f32_e32 v14, v106
	v_exp_f32_e32 v15, v107
	v_exp_f32_e32 v106, v108
	v_exp_f32_e32 v107, v109
	v_exp_f32_e32 v108, v126
	v_exp_f32_e32 v109, v127
	v_exp_f32_e32 v126, v128
	v_exp_f32_e32 v127, v129
	v_exp_f32_e32 v128, v134
	v_exp_f32_e32 v131, v136
	v_exp_f32_e32 v134, v137
	v_exp_f32_e32 v154, v154
	v_exp_f32_e32 v155, v155
	v_exp_f32_e32 v156, v156
	v_exp_f32_e32 v157, v157
	v_exp_f32_e32 v129, v135
	v_cvt_pk_bf16_f32 v10, v10, v11
	v_cvt_pk_bf16_f32 v11, v12, v13
	v_cvt_pk_bf16_f32 v12, v14, v15
	v_cvt_pk_bf16_f32 v13, v106, v107
	v_cvt_pk_bf16_f32 v106, v108, v109
	v_cvt_pk_bf16_f32 v107, v126, v127
	v_cvt_pk_bf16_f32 v109, v131, v134
	v_cvt_pk_bf16_f32 v131, v132, v133
	v_cvt_pk_bf16_f32 v132, v146, v147
	v_cvt_pk_bf16_f32 v133, v148, v149
	v_exp_f32_e32 v126, v16
	v_exp_f32_e32 v17, v17
	s_bitcmp1_b32 s41, 8
	s_cbranch_scc0 .Lml_h1p2_end
	s_add_i32 s99, s20, -2
	s_cmp_ge_u32 s99, s18
	s_cbranch_scc1 .Lml_h1p2_bar
	s_waitcnt vmcnt(5)
	ds_write_b128 v208, v[78:81]
	s_and_saveexec_b64 s[100:101], s[4:5]
	s_cbranch_execz .Lml_h1p2_w
	v_add_u32_e32 v232, 0, v209
	s_waitcnt vmcnt(3)
	ds_write_b128 v232, v[86:89] offset:2048
